# GEMM1 epilogue rope section: 10 table loads issued up front with counted waits (prologue/epilogue de-serialisation lever)
# speedup vs baseline: 1.0040x; 1.0025x over previous
.LBB0_353:
	s_cmp_gt_u32 s22, 63
	s_movk_i32 s6, 0x200
	s_cselect_b64 s[2:3], -1, 0
	v_cmp_gt_i32_e32 vcc, s6, v94
	s_and_b64 s[6:7], s[2:3], vcc
	v_lshlrev_b32_e32 v95, 2, v2
	s_and_saveexec_b64 s[2:3], s[6:7]
	s_cbranch_execz .LBB0_355
	s_lshl_b32 s6, s22, 5
	v_lshl_add_u32 v2, v92, 4, s6
	v_and_b32_e32 v2, 0x1f0, v2
	v_lshlrev_b32_e32 v2, 2, v2
	v_lshl_add_u64 v[56:57], s[42:43], 0, v[2:3]
	v_lshlrev_b32_e32 v58, 2, v95
	v_mov_b32_e32 v59, v3
	v_readlane_b32 s6, v254, 48
	v_lshl_add_u64 v[56:57], v[56:57], 0, v[58:59]
	v_readlane_b32 s7, v254, 49
	global_load_dwordx4 v[76:79], v[56:57], off
	s_nop 0
	v_lshl_add_u64 v[56:57], s[6:7], 0, v[2:3]
	v_lshl_add_u64 v[56:57], v[56:57], 0, v[58:59]
	global_load_dwordx4 v[80:83], v[56:57], off
	v_lshl_add_u64 v[56:57], s[42:43], 0, v[58:59]
	v_lshl_add_u64 v[58:59], s[6:7], 0, v[58:59]
	v_lshlrev_b32_e32 v2, 6, v93
	v_lshl_add_u64 v[90:91], v[56:57], 0, v[2:3]
	v_lshl_add_u64 v[88:89], v[58:59], 0, v[2:3]
	global_load_dwordx4 v[64:67], v[90:91], off
	global_load_dwordx4 v[84:87], v[88:89], off
	global_load_dwordx4 v[140:143], v[90:91], off offset:1024
	global_load_dwordx4 v[144:147], v[88:89], off offset:1024
	global_load_dwordx4 v[148:151], v[90:91], off offset:2048
	global_load_dwordx4 v[152:155], v[88:89], off offset:2048
	global_load_dwordx4 v[156:159], v[90:91], off offset:3072
	global_load_dwordx4 v[160:163], v[88:89], off offset:3072
	s_waitcnt vmcnt(8)
	v_pk_mul_f32 v[56:57], v[34:35], v[82:83]
	v_pk_mul_f32 v[96:97], v[32:33], v[80:81]
	v_pk_fma_f32 v[58:59], v[62:63], v[78:79], v[56:57] neg_lo:[0,0,1] neg_hi:[0,0,1]
	v_pk_fma_f32 v[56:57], v[60:61], v[76:77], v[96:97] neg_lo:[0,0,1] neg_hi:[0,0,1]
	v_pk_mul_f32 v[60:61], v[60:61], v[80:81]
	v_pk_mul_f32 v[62:63], v[62:63], v[82:83]
	v_pk_fma_f32 v[32:33], v[32:33], v[76:77], v[60:61]
	s_waitcnt vmcnt(6)
	v_pk_mul_f32 v[60:61], v[18:19], v[86:87]
	v_pk_mul_f32 v[96:97], v[16:17], v[84:85]
	v_pk_fma_f32 v[34:35], v[34:35], v[78:79], v[62:63]
	v_pk_fma_f32 v[62:63], v[74:75], v[66:67], v[60:61] neg_lo:[0,0,1] neg_hi:[0,0,1]
	v_pk_fma_f32 v[60:61], v[72:73], v[64:65], v[96:97] neg_lo:[0,0,1] neg_hi:[0,0,1]
	v_pk_mul_f32 v[74:75], v[74:75], v[86:87]
	v_pk_mul_f32 v[72:73], v[72:73], v[84:85]
	v_pk_fma_f32 v[18:19], v[18:19], v[66:67], v[74:75]
	v_pk_fma_f32 v[16:17], v[16:17], v[64:65], v[72:73]
	v_pk_mul_f32 v[64:65], v[30:31], v[82:83]
	v_pk_mul_f32 v[96:97], v[28:29], v[80:81]
	v_pk_fma_f32 v[66:67], v[70:71], v[78:79], v[64:65] neg_lo:[0,0,1] neg_hi:[0,0,1]
	v_pk_fma_f32 v[64:65], v[68:69], v[76:77], v[96:97] neg_lo:[0,0,1] neg_hi:[0,0,1]
	v_pk_mul_f32 v[68:69], v[68:69], v[80:81]
	v_pk_mul_f32 v[70:71], v[70:71], v[82:83]
	v_pk_fma_f32 v[28:29], v[28:29], v[76:77], v[68:69]
	v_pk_fma_f32 v[30:31], v[30:31], v[78:79], v[70:71]
	s_waitcnt vmcnt(4)
	v_pk_mul_f32 v[68:69], v[14:15], v[146:147]
	v_pk_mul_f32 v[96:97], v[12:13], v[144:145]
	v_pk_fma_f32 v[70:71], v[50:51], v[142:143], v[68:69] neg_lo:[0,0,1] neg_hi:[0,0,1]
	v_pk_fma_f32 v[68:69], v[48:49], v[140:141], v[96:97] neg_lo:[0,0,1] neg_hi:[0,0,1]
	v_pk_mul_f32 v[50:51], v[50:51], v[146:147]
	v_pk_mul_f32 v[48:49], v[48:49], v[144:145]
	v_pk_fma_f32 v[14:15], v[14:15], v[142:143], v[50:51]
	v_pk_fma_f32 v[12:13], v[12:13], v[140:141], v[48:49]
	v_pk_mul_f32 v[48:49], v[26:27], v[82:83]
	v_pk_mul_f32 v[50:51], v[24:25], v[80:81]
	v_pk_fma_f32 v[86:87], v[54:55], v[78:79], v[48:49] neg_lo:[0,0,1] neg_hi:[0,0,1]
	v_pk_mul_f32 v[48:49], v[54:55], v[82:83]
	v_pk_fma_f32 v[84:85], v[52:53], v[76:77], v[50:51] neg_lo:[0,0,1] neg_hi:[0,0,1]
	v_pk_mul_f32 v[50:51], v[52:53], v[80:81]
	v_pk_fma_f32 v[26:27], v[26:27], v[78:79], v[48:49]
	v_pk_fma_f32 v[24:25], v[24:25], v[76:77], v[50:51]
	s_waitcnt vmcnt(2)
	v_pk_mul_f32 v[48:49], v[10:11], v[154:155]
	v_pk_mul_f32 v[52:53], v[8:9], v[152:153]
	v_pk_fma_f32 v[50:51], v[46:47], v[150:151], v[48:49] neg_lo:[0,0,1] neg_hi:[0,0,1]
	v_pk_fma_f32 v[48:49], v[44:45], v[148:149], v[52:53] neg_lo:[0,0,1] neg_hi:[0,0,1]
	v_pk_mul_f32 v[46:47], v[46:47], v[154:155]
	v_pk_mul_f32 v[44:45], v[44:45], v[152:153]
	v_pk_fma_f32 v[10:11], v[10:11], v[150:151], v[46:47]
	v_pk_fma_f32 v[8:9], v[8:9], v[148:149], v[44:45]
	v_pk_mul_f32 v[74:75], v[20:21], v[80:81]
	v_pk_mul_f32 v[72:73], v[22:23], v[82:83]
	v_pk_fma_f32 v[88:89], v[40:41], v[76:77], v[74:75] neg_lo:[0,0,1] neg_hi:[0,0,1]
	v_pk_mul_f32 v[40:41], v[40:41], v[80:81]
	v_pk_fma_f32 v[90:91], v[42:43], v[78:79], v[72:73] neg_lo:[0,0,1] neg_hi:[0,0,1]
	v_pk_mul_f32 v[42:43], v[42:43], v[82:83]
	v_pk_fma_f32 v[20:21], v[20:21], v[76:77], v[40:41]
	v_pk_fma_f32 v[22:23], v[22:23], v[78:79], v[42:43]
	s_waitcnt vmcnt(0)
	v_pk_mul_f32 v[40:41], v[6:7], v[162:163]
	v_pk_mul_f32 v[72:73], v[4:5], v[160:161]
	v_pk_fma_f32 v[42:43], v[38:39], v[158:159], v[40:41] neg_lo:[0,0,1] neg_hi:[0,0,1]
	v_pk_fma_f32 v[40:41], v[36:37], v[156:157], v[72:73] neg_lo:[0,0,1] neg_hi:[0,0,1]
	v_pk_mul_f32 v[38:39], v[38:39], v[162:163]
	v_pk_mul_f32 v[36:37], v[36:37], v[160:161]
	v_pk_fma_f32 v[6:7], v[6:7], v[158:159], v[38:39]
	v_pk_fma_f32 v[4:5], v[4:5], v[156:157], v[36:37]
	v_mov_b64_e32 v[44:45], v[48:49]
	v_mov_b64_e32 v[36:37], v[40:41]
	v_mov_b64_e32 v[46:47], v[50:51]
	v_mov_b64_e32 v[48:49], v[68:69]
	v_mov_b64_e32 v[74:75], v[62:63]
	v_mov_b64_e32 v[38:39], v[42:43]
	v_mov_b64_e32 v[50:51], v[70:71]
	v_mov_b64_e32 v[72:73], v[60:61]
	v_mov_b64_e32 v[40:41], v[88:89]
	v_mov_b64_e32 v[52:53], v[84:85]
	v_mov_b64_e32 v[70:71], v[66:67]
	v_mov_b64_e32 v[62:63], v[58:59]
	v_mov_b64_e32 v[42:43], v[90:91]
	v_mov_b64_e32 v[54:55], v[86:87]
	v_mov_b64_e32 v[68:69], v[64:65]
	v_mov_b64_e32 v[60:61], v[56:57]
